# adds: P0/XN1 loads the rmsnorm gain once before the loop instead of 16x per iteration (removes a vmcnt(0) store drain before every store)
# baseline (speedup 1.0000x reference)
; __device__ __forceinline__ unsigned pk2(float lo, float hi) { return f2bf(lo) | (f2bf(hi) << 16); }
; __device__ __forceinline__ void p0_prologue(const Params& p, LAS unsigned char* lds, int G) {
;     ...
;     bf16_t* XN = (bf16_t*)(p.ws + WS_ACTA);
;     const f32x4* gp = (const f32x4*)p.in[2] + lane;
;     for (int rb = gw * 4; rb < T; rb += NGW * 4) {
;         f32x4 v[4][4]; float s[4];
; #pragma unroll
;         for (int q = 0; q < 4; ++q) { const int row = rb + q; const float* xrow = row < TP ? p.in[0] + (size_t)row * D : p.in[1] + (size_t)(row - TP) * D; const f32x4* xr = (const f32x4*)xrow + lane;
; #pragma unroll
;             for (int j = 0; j < 4; ++j) v[q][j] = xr[64 * j]; }
; #pragma unroll
;         for (int q = 0; q < 4; ++q) { float a = 0.f;
; #pragma unroll
;             for (int j = 0; j < 4; ++j) a += (v[q][j][0] * v[q][j][0] + v[q][j][1] * v[q][j][1]) + (v[q][j][2] * v[q][j][2] + v[q][j][3] * v[q][j][3]);
;             s[q] = a; }
; #pragma unroll
;         for (int q = 0; q < 4; ++q) { const float rstd = __builtin_amdgcn_rsqf(wave_sum(s[q]) * (1.f / D) + EPS);
;             u32x2* o8 = (u32x2*)(XN + (size_t)(rb + q) * D) + lane;
; #pragma unroll
;             for (int j = 0; j < 4; ++j) { const f32x4 g = gp[64 * j]; u32x2 w; w.x = pk2(v[q][j][0] * rstd * g[0], v[q][j][1] * rstd * g[1]); w.y = pk2(v[q][j][2] * rstd * g[2], v[q][j][3] * rstd * g[3]); o8[64 * j] = w; } }
.LBB0_169:
	s_or_b64 exec, exec, s[16:17]
	s_movk_i32 s0, 0x3000
	v_cmp_gt_i32_e32 vcc, s0, v1
	s_and_saveexec_b64 s[4:5], vcc
	s_cbranch_execz .LBB0_174
	v_lshlrev_b32_e32 v66, 2, v1
	v_mbcnt_lo_u32_b32 v1, -1, 0
	v_mbcnt_hi_u32_b32 v1, -1, v1
	v_and_b32_e32 v2, 64, v1
	v_add_u32_e32 v2, 64, v2
	v_xor_b32_e32 v3, 1, v1
	v_cmp_lt_i32_e32 vcc, v3, v2
	s_load_dwordx2 s[6:7], s[88:89], 0x10
	s_load_dwordx4 s[0:3], s[88:89], 0x0
	v_cndmask_b32_e32 v3, v1, v3, vcc
	v_lshlrev_b32_e32 v80, 2, v3
	v_xor_b32_e32 v3, 2, v1
	v_cmp_lt_i32_e32 vcc, v3, v2
	v_mov_b32_e32 v65, 0
	v_lshlrev_b32_e32 v64, 4, v0
	v_cndmask_b32_e32 v3, v1, v3, vcc
	v_lshlrev_b32_e32 v81, 2, v3
	v_xor_b32_e32 v3, 4, v1
	v_cmp_lt_i32_e32 vcc, v3, v2
	s_waitcnt lgkmcnt(0)
	v_lshl_add_u64 v[68:69], s[6:7], 0, v[64:65]
	global_load_dwordx4 v[112:115], v[68:69], off
	global_load_dwordx4 v[116:119], v[68:69], off offset:1024
	global_load_dwordx4 v[120:123], v[68:69], off offset:2048
	global_load_dwordx4 v[124:127], v[68:69], off offset:3072
	s_waitcnt vmcnt(0)
	v_lshlrev_b32_e32 v64, 3, v0
	v_cndmask_b32_e32 v3, v1, v3, vcc
	v_lshlrev_b32_e32 v82, 2, v3
	v_xor_b32_e32 v3, 8, v1
	v_cmp_lt_i32_e32 vcc, v3, v2
	s_mov_b64 s[6:7], 0x3000000
	v_ashrrev_i32_e32 v67, 31, v66
	v_cndmask_b32_e32 v3, v1, v3, vcc
	v_lshlrev_b32_e32 v83, 2, v3
	v_xor_b32_e32 v3, 16, v1
	v_cmp_lt_i32_e32 vcc, v3, v2
	s_mov_b64 s[8:9], 0x3000
	s_mov_b64 s[10:11], 0x3001600
	v_cndmask_b32_e32 v3, v1, v3, vcc
	v_lshlrev_b32_e32 v84, 2, v3
	v_xor_b32_e32 v3, 32, v1
	v_cmp_lt_i32_e32 vcc, v3, v2
	v_or_b32_e32 v72, 1, v66
	v_mov_b32_e32 v73, v67
	v_cndmask_b32_e32 v1, v1, v3, vcc
	v_lshl_add_u64 v[2:3], s[92:93], 0, v[64:65]
	v_lshl_add_u64 v[70:71], v[2:3], 0, s[6:7]
	v_lshlrev_b64 v[2:3], 12, v[66:67]
	v_lshl_add_u64 v[2:3], s[0:1], 0, v[2:3]
	v_lshl_add_u64 v[74:75], v[2:3], 0, s[8:9]
	v_lshlrev_b64 v[2:3], 11, v[66:67]
	s_lshl_b32 s6, s86, 5
	v_or_b32_e32 v2, v2, v64
	s_ashr_i32 s7, s6, 31
	v_lshl_add_u64 v[2:3], s[92:93], 0, v[2:3]
	v_lshlrev_b32_e32 v85, 2, v1
	s_lshl_b64 s[8:9], s[6:7], 12
	v_lshl_add_u64 v[76:77], v[2:3], 0, s[10:11]
	s_lshl_b64 s[10:11], s[6:7], 11
	s_mov_b64 s[16:17], 0
	s_mov_b32 s18, 0x8000
	v_mov_b32_e32 v67, s3
	v_mov_b32_e32 v86, s1
	v_mov_b32_e32 v87, s2
	v_mov_b32_e32 v88, s0
	v_lshlrev_b32_e32 v64, 4, v0
	s_movk_i32 s19, 0x7fff
	v_mov_b32_e32 v89, 0x358637bd
	s_movk_i32 s20, 0xf000
	s_mov_b32 s21, 0xbfff
	v_mov_b32_e32 v90, 1
	s_branch .LBB0_172
.LBB0_171:
	s_or_b64 exec, exec, s[0:1]
	v_mov_b32_e32 v92, v112
	v_mov_b32_e32 v93, v113
	v_mov_b32_e32 v94, v114
	v_mov_b32_e32 v95, v115
	s_waitcnt vmcnt(11)
	v_pk_mul_f32 v[14:15], v[62:63], v[62:63]
	v_pk_mul_f32 v[20:21], v[60:61], v[60:61]
	s_waitcnt vmcnt(10)
	v_pk_mul_f32 v[22:23], v[58:59], v[58:59]
	v_pk_mul_f32 v[24:25], v[56:57], v[56:57]
	v_pk_mov_b32 v[34:35], v[20:21], v[14:15] op_sel:[1,0]
	v_mov_b32_e32 v21, v15
	v_pk_mov_b32 v[14:15], v[24:25], v[22:23] op_sel:[1,0]
	v_mov_b32_e32 v25, v23
	s_waitcnt vmcnt(8)
	v_mul_f32_e32 v33, v48, v48
	v_mul_f32_e32 v26, v53, v53
	v_mul_f32_e32 v32, v55, v55
	v_pk_add_f32 v[20:21], v[34:35], v[20:21]
	v_pk_add_f32 v[14:15], v[14:15], v[24:25]
	v_mul_f32_e32 v91, v49, v49
	v_mul_f32_e32 v96, v50, v50
	v_mul_f32_e32 v97, v51, v51
	v_pk_fma_f32 v[22:23], v[52:53], v[52:53], v[26:27] op_sel_hi:[1,1,0]
	v_pk_fma_f32 v[26:27], v[54:55], v[54:55], v[32:33] op_sel_hi:[1,1,0]
	v_pk_add_f32 v[20:21], v[20:21], v[20:21] op_sel:[0,1] op_sel_hi:[1,0]
	v_pk_add_f32 v[14:15], v[14:15], v[14:15] op_sel:[0,1] op_sel_hi:[1,0]
	v_mov_b32_e32 v23, v96
	v_mov_b32_e32 v27, v97
	v_mov_b32_e32 v21, v33
	v_mov_b32_e32 v15, v91
	v_pk_add_f32 v[22:23], v[22:23], v[26:27]
	v_pk_add_f32 v[14:15], v[20:21], v[14:15]
	v_lshl_add_u64 v[96:97], v[12:13], 0, v[64:65]
	v_pk_add_f32 v[14:15], v[14:15], v[22:23]
	v_mov_b32_e32 v99, v62
	v_add_f32_e32 v14, v14, v15
	ds_bpermute_b32 v15, v80, v14
	v_mov_b32_e32 v62, v61
	v_mov_b32_e32 v98, v60
	v_add_co_u32_e32 v100, vcc, s20, v76
	s_waitcnt lgkmcnt(0)
	v_add_f32_e32 v14, v14, v15
	ds_bpermute_b32 v15, v81, v14
	v_addc_co_u32_e32 v101, vcc, -1, v77, vcc
	v_add_u32_e32 v66, s6, v66
	v_cmp_lt_i32_e32 vcc, s21, v66
	s_waitcnt lgkmcnt(0)
	v_add_f32_e32 v14, v14, v15
	ds_bpermute_b32 v15, v82, v14
	v_lshl_add_u64 v[72:73], v[72:73], 0, s[6:7]
	v_lshl_add_u64 v[74:75], v[74:75], 0, s[8:9]
	s_or_b64 s[16:17], vcc, s[16:17]
	s_waitcnt lgkmcnt(0)
	v_add_f32_e32 v14, v14, v15
	ds_bpermute_b32 v15, v83, v14
	s_waitcnt lgkmcnt(0)
	v_add_f32_e32 v14, v14, v15
	ds_bpermute_b32 v15, v84, v14
	s_waitcnt lgkmcnt(0)
	v_add_f32_e32 v12, v14, v15
	ds_bpermute_b32 v13, v85, v12
	s_waitcnt lgkmcnt(0)
	v_add_f32_e32 v12, v12, v13
	v_fmamk_f32 v12, v12, 0x3a800000, v89
	v_rsq_f32_e32 v102, v12
	global_load_dwordx4 v[32:35], v[96:97], off
	global_load_dwordx4 v[24:27], v[96:97], off offset:1024
	global_load_dwordx4 v[20:23], v[96:97], off offset:2048
	global_load_dwordx4 v[12:15], v[96:97], off offset:3072
	v_pk_mul_f32 v[62:63], v[62:63], v[102:103] op_sel_hi:[1,0]
	v_pk_mul_f32 v[60:61], v[98:99], v[102:103] op_sel_hi:[1,0]
	s_waitcnt vmcnt(4)
; __device__ __forceinline__ unsigned pk2(float lo, float hi) { return f2bf(lo) | (f2bf(hi) << 16); }
; __device__ __forceinline__ void p0_prologue(const Params& p, LAS unsigned char* lds, int G) {
;     ...
;         for (int q = 0; q < 4; ++q) { float a = 0.f;
; #pragma unroll
;             for (int j = 0; j < 4; ++j) a += (v[q][j][0] * v[q][j][0] + v[q][j][1] * v[q][j][1]) + (v[q][j][2] * v[q][j][2] + v[q][j][3] * v[q][j][3]);
;             s[q] = a; }
; #pragma unroll
;         for (int q = 0; q < 4; ++q) { const float rstd = __builtin_amdgcn_rsqf(wave_sum(s[q]) * (1.f / D) + EPS);
;             u32x2* o8 = (u32x2*)(XN + (size_t)(rb + q) * D) + lane;
; #pragma unroll
;             for (int j = 0; j < 4; ++j) { const f32x4 g = gp[64 * j]; u32x2 w; w.x = pk2(v[q][j][0] * rstd * g[0], v[q][j][1] * rstd * g[1]); w.y = pk2(v[q][j][2] * rstd * g[2], v[q][j][3] * rstd * g[3]); o8[64 * j] = w; } }
	v_mov_b32_e32 v97, v94
	v_mov_b32_e32 v94, v93
	v_mov_b32_e32 v96, v92
	v_pk_mul_f32 v[62:63], v[94:95], v[62:63]
	v_pk_mul_f32 v[60:61], v[96:97], v[60:61]
	v_and_b32_sdwa v93, v63, v90 dst_sel:DWORD dst_unused:UNUSED_PAD src0_sel:WORD_1 src1_sel:DWORD
	v_and_b32_sdwa v94, v62, v90 dst_sel:DWORD dst_unused:UNUSED_PAD src0_sel:WORD_1 src1_sel:DWORD
	v_and_b32_sdwa v91, v61, v90 dst_sel:DWORD dst_unused:UNUSED_PAD src0_sel:WORD_1 src1_sel:DWORD
	v_and_b32_sdwa v92, v60, v90 dst_sel:DWORD dst_unused:UNUSED_PAD src0_sel:WORD_1 src1_sel:DWORD
	v_add3_u32 v63, v63, v93, s19
	v_add3_u32 v62, v62, v94, s19
	v_add3_u32 v60, v60, v92, s19
	v_add3_u32 v61, v61, v91, s19
	v_and_b32_e32 v63, 0xffff0000, v63
	v_and_b32_e32 v62, 0xffff0000, v62
	v_or_b32_sdwa v61, v63, v61 dst_sel:DWORD dst_unused:UNUSED_PAD src0_sel:DWORD src1_sel:WORD_1
	v_or_b32_sdwa v60, v62, v60 dst_sel:DWORD dst_unused:UNUSED_PAD src0_sel:DWORD src1_sel:WORD_1
	global_store_dwordx2 v[100:101], v[60:61], off offset:-1536
	v_mov_b32_e32 v60, v116
	v_mov_b32_e32 v61, v117
	v_mov_b32_e32 v62, v118
	v_mov_b32_e32 v63, v119
	v_mov_b32_e32 v92, v56
	v_mov_b32_e32 v93, v58
	v_mov_b32_e32 v58, v57
	v_pk_mul_f32 v[56:57], v[92:93], v[102:103] op_sel_hi:[1,0]
	v_pk_mul_f32 v[58:59], v[58:59], v[102:103] op_sel_hi:[1,0]
	v_mul_f32_e32 v91, v29, v29
	v_mul_f32_e32 v94, v30, v30
	v_mul_f32_e32 v95, v31, v31
	s_waitcnt vmcnt(1)
	v_mov_b32_e32 v93, v62
	v_mov_b32_e32 v62, v61
	v_mov_b32_e32 v92, v60
	v_pk_mul_f32 v[58:59], v[62:63], v[58:59]
	v_pk_mul_f32 v[56:57], v[92:93], v[56:57]
	v_and_b32_sdwa v62, v59, v90 dst_sel:DWORD dst_unused:UNUSED_PAD src0_sel:WORD_1 src1_sel:DWORD
	v_and_b32_sdwa v63, v58, v90 dst_sel:DWORD dst_unused:UNUSED_PAD src0_sel:WORD_1 src1_sel:DWORD
	v_and_b32_sdwa v60, v57, v90 dst_sel:DWORD dst_unused:UNUSED_PAD src0_sel:WORD_1 src1_sel:DWORD
	v_and_b32_sdwa v61, v56, v90 dst_sel:DWORD dst_unused:UNUSED_PAD src0_sel:WORD_1 src1_sel:DWORD
	v_add3_u32 v59, v59, v62, s19
	v_add3_u32 v58, v58, v63, s19
	v_add3_u32 v56, v56, v61, s19
	v_add3_u32 v57, v57, v60, s19
	v_and_b32_e32 v59, 0xffff0000, v59
	v_and_b32_e32 v58, 0xffff0000, v58
	v_or_b32_sdwa v57, v59, v57 dst_sel:DWORD dst_unused:UNUSED_PAD src0_sel:DWORD src1_sel:WORD_1
	v_or_b32_sdwa v56, v58, v56 dst_sel:DWORD dst_unused:UNUSED_PAD src0_sel:DWORD src1_sel:WORD_1
	global_store_dwordx2 v[100:101], v[56:57], off offset:-1024
	v_mov_b32_e32 v56, v120
	v_mov_b32_e32 v57, v121
	v_mov_b32_e32 v58, v122
	v_mov_b32_e32 v59, v123
	v_mov_b32_e32 v60, v52
	v_mov_b32_e32 v61, v54
	v_mov_b32_e32 v54, v53
	v_pk_mul_f32 v[52:53], v[60:61], v[102:103] op_sel_hi:[1,0]
	v_pk_mul_f32 v[54:55], v[54:55], v[102:103] op_sel_hi:[1,0]
	v_mul_f32_e32 v63, v28, v28
	v_mul_f32_e32 v62, v39, v39
	v_mov_b32_e32 v61, v58
	v_mov_b32_e32 v58, v57
	v_mov_b32_e32 v60, v56
	v_pk_mul_f32 v[54:55], v[58:59], v[54:55]
	v_pk_mul_f32 v[52:53], v[60:61], v[52:53]
	v_and_b32_sdwa v58, v55, v90 dst_sel:DWORD dst_unused:UNUSED_PAD src0_sel:WORD_1 src1_sel:DWORD
	v_and_b32_sdwa v59, v54, v90 dst_sel:DWORD dst_unused:UNUSED_PAD src0_sel:WORD_1 src1_sel:DWORD
	v_and_b32_sdwa v56, v53, v90 dst_sel:DWORD dst_unused:UNUSED_PAD src0_sel:WORD_1 src1_sel:DWORD
	v_and_b32_sdwa v57, v52, v90 dst_sel:DWORD dst_unused:UNUSED_PAD src0_sel:WORD_1 src1_sel:DWORD
	v_add3_u32 v55, v55, v58, s19
	v_add3_u32 v54, v54, v59, s19
	v_add3_u32 v52, v52, v57, s19
	v_add3_u32 v53, v53, v56, s19
	v_and_b32_e32 v55, 0xffff0000, v55
	v_and_b32_e32 v54, 0xffff0000, v54
	v_or_b32_sdwa v53, v55, v53 dst_sel:DWORD dst_unused:UNUSED_PAD src0_sel:DWORD src1_sel:WORD_1
	v_or_b32_sdwa v52, v54, v52 dst_sel:DWORD dst_unused:UNUSED_PAD src0_sel:DWORD src1_sel:WORD_1
	global_store_dwordx2 v[100:101], v[52:53], off offset:-512
	v_mov_b32_e32 v52, v124
	v_mov_b32_e32 v53, v125
	v_mov_b32_e32 v54, v126
	v_mov_b32_e32 v55, v127
	v_mov_b32_e32 v56, v48
	v_mov_b32_e32 v57, v50
	v_mov_b32_e32 v50, v49
	v_pk_mul_f32 v[48:49], v[56:57], v[102:103] op_sel_hi:[1,0]
	v_pk_mul_f32 v[50:51], v[50:51], v[102:103] op_sel_hi:[1,0]
	v_pk_mul_f32 v[58:59], v[40:41], v[40:41]
	v_mul_f32_e32 v60, v37, v37
	v_mov_b32_e32 v57, v54
	v_mov_b32_e32 v54, v53
	v_mov_b32_e32 v56, v52
	v_pk_mul_f32 v[50:51], v[50:51], v[54:55]
	v_pk_mul_f32 v[48:49], v[48:49], v[56:57]
	v_and_b32_sdwa v54, v51, v90 dst_sel:DWORD dst_unused:UNUSED_PAD src0_sel:WORD_1 src1_sel:DWORD
	v_and_b32_sdwa v55, v50, v90 dst_sel:DWORD dst_unused:UNUSED_PAD src0_sel:WORD_1 src1_sel:DWORD
	v_and_b32_sdwa v52, v49, v90 dst_sel:DWORD dst_unused:UNUSED_PAD src0_sel:WORD_1 src1_sel:DWORD
	v_and_b32_sdwa v53, v48, v90 dst_sel:DWORD dst_unused:UNUSED_PAD src0_sel:WORD_1 src1_sel:DWORD
	v_add3_u32 v51, v51, v54, s19
	v_add3_u32 v50, v50, v55, s19
	v_add3_u32 v48, v48, v53, s19
	v_add3_u32 v49, v49, v52, s19
	v_and_b32_e32 v51, 0xffff0000, v51
	v_and_b32_e32 v50, 0xffff0000, v50
	v_or_b32_sdwa v49, v51, v49 dst_sel:DWORD dst_unused:UNUSED_PAD src0_sel:DWORD src1_sel:WORD_1
	v_or_b32_sdwa v48, v50, v48 dst_sel:DWORD dst_unused:UNUSED_PAD src0_sel:DWORD src1_sel:WORD_1
	global_store_dwordx2 v[76:77], v[48:49], off offset:-4096
	v_mov_b32_e32 v48, v112
	v_mov_b32_e32 v49, v113
	v_mov_b32_e32 v50, v114
	v_mov_b32_e32 v51, v115
	v_pk_mul_f32 v[52:53], v[46:47], v[46:47]
	v_pk_mul_f32 v[54:55], v[44:45], v[44:45]
	v_pk_mul_f32 v[56:57], v[42:43], v[42:43]
	v_pk_mov_b32 v[92:93], v[54:55], v[52:53] op_sel:[1,0]
	v_mov_b32_e32 v55, v53
	v_pk_mov_b32 v[52:53], v[58:59], v[56:57] op_sel:[1,0]
	v_mov_b32_e32 v59, v57
	v_pk_add_f32 v[54:55], v[92:93], v[54:55]
	v_pk_add_f32 v[52:53], v[52:53], v[58:59]
	v_pk_fma_f32 v[56:57], v[36:37], v[36:37], v[60:61] op_sel_hi:[1,1,0]
	v_pk_fma_f32 v[60:61], v[38:39], v[38:39], v[62:63] op_sel_hi:[1,1,0]
	v_pk_add_f32 v[54:55], v[54:55], v[54:55] op_sel:[0,1] op_sel_hi:[1,0]
	v_pk_add_f32 v[52:53], v[52:53], v[52:53] op_sel:[0,1] op_sel_hi:[1,0]
	v_mov_b32_e32 v57, v94
	v_mov_b32_e32 v61, v95
	v_mov_b32_e32 v55, v63
	v_mov_b32_e32 v53, v91
	v_pk_add_f32 v[56:57], v[56:57], v[60:61]
	v_pk_add_f32 v[52:53], v[54:55], v[52:53]
	v_mov_b32_e32 v54, v44
	v_pk_add_f32 v[52:53], v[52:53], v[56:57]
	v_mov_b32_e32 v55, v46
	v_add_f32_e32 v52, v52, v53
	ds_bpermute_b32 v53, v80, v52
	v_mov_b32_e32 v46, v45
	s_waitcnt lgkmcnt(0)
; __device__ __forceinline__ unsigned pk2(float lo, float hi) { return f2bf(lo) | (f2bf(hi) << 16); }
; __device__ __forceinline__ float wave_sum(float v) {
; #pragma unroll
;     for (int o = 1; o < 64; o <<= 1) v += __shfl_xor(v, o);
;     return v;
; __device__ __forceinline__ void p0_prologue(const Params& p, LAS unsigned char* lds, int G) {
;     ...
;         for (int q = 0; q < 4; ++q) { const float rstd = __builtin_amdgcn_rsqf(wave_sum(s[q]) * (1.f / D) + EPS);
;             u32x2* o8 = (u32x2*)(XN + (size_t)(rb + q) * D) + lane;
; #pragma unroll
;             for (int j = 0; j < 4; ++j) { const f32x4 g = gp[64 * j]; u32x2 w; w.x = pk2(v[q][j][0] * rstd * g[0], v[q][j][1] * rstd * g[1]); w.y = pk2(v[q][j][2] * rstd * g[2], v[q][j][3] * rstd * g[3]); o8[64 * j] = w; } }
	v_add_f32_e32 v52, v52, v53
	ds_bpermute_b32 v53, v81, v52
	s_waitcnt lgkmcnt(0)
	v_add_f32_e32 v52, v52, v53
	ds_bpermute_b32 v53, v82, v52
	s_waitcnt lgkmcnt(0)
	v_add_f32_e32 v52, v52, v53
	ds_bpermute_b32 v53, v83, v52
	s_waitcnt lgkmcnt(0)
	v_add_f32_e32 v52, v52, v53
	ds_bpermute_b32 v53, v84, v52
	s_waitcnt lgkmcnt(0)
	v_add_f32_e32 v52, v52, v53
	ds_bpermute_b32 v53, v85, v52
	s_waitcnt lgkmcnt(0)
	v_add_f32_e32 v52, v52, v53
	v_fmamk_f32 v52, v52, 0x3a800000, v89
	v_rsq_f32_e32 v52, v52
	s_nop 0
	v_pk_mul_f32 v[44:45], v[54:55], v[52:53] op_sel_hi:[1,0]
	v_pk_mul_f32 v[46:47], v[46:47], v[52:53] op_sel_hi:[1,0]
	v_mov_b32_e32 v55, v50
	v_mov_b32_e32 v50, v49
	v_mov_b32_e32 v54, v48
	v_pk_mul_f32 v[46:47], v[50:51], v[46:47]
	v_pk_mul_f32 v[44:45], v[54:55], v[44:45]
	v_and_b32_sdwa v50, v47, v90 dst_sel:DWORD dst_unused:UNUSED_PAD src0_sel:WORD_1 src1_sel:DWORD
	v_and_b32_sdwa v51, v46, v90 dst_sel:DWORD dst_unused:UNUSED_PAD src0_sel:WORD_1 src1_sel:DWORD
	v_and_b32_sdwa v48, v45, v90 dst_sel:DWORD dst_unused:UNUSED_PAD src0_sel:WORD_1 src1_sel:DWORD
	v_and_b32_sdwa v49, v44, v90 dst_sel:DWORD dst_unused:UNUSED_PAD src0_sel:WORD_1 src1_sel:DWORD
	v_add3_u32 v47, v47, v50, s19
	v_add3_u32 v46, v46, v51, s19
	v_add3_u32 v44, v44, v49, s19
	v_add3_u32 v45, v45, v48, s19
	v_and_b32_e32 v47, 0xffff0000, v47
	v_and_b32_e32 v46, 0xffff0000, v46
	v_or_b32_sdwa v45, v47, v45 dst_sel:DWORD dst_unused:UNUSED_PAD src0_sel:DWORD src1_sel:WORD_1
	v_or_b32_sdwa v44, v46, v44 dst_sel:DWORD dst_unused:UNUSED_PAD src0_sel:DWORD src1_sel:WORD_1
	global_store_dwordx2 v[76:77], v[44:45], off offset:-3584
	v_mov_b32_e32 v44, v116
	v_mov_b32_e32 v45, v117
	v_mov_b32_e32 v46, v118
	v_mov_b32_e32 v47, v119
	v_mov_b32_e32 v48, v40
	v_mov_b32_e32 v49, v42
	v_mov_b32_e32 v42, v41
	v_pk_mul_f32 v[40:41], v[48:49], v[52:53] op_sel_hi:[1,0]
	v_pk_mul_f32 v[42:43], v[42:43], v[52:53] op_sel_hi:[1,0]
	v_mul_f32_e32 v50, v1, v1
	v_mul_f32_e32 v51, v2, v2
	v_mov_b32_e32 v49, v46
	v_mov_b32_e32 v46, v45
	v_mov_b32_e32 v48, v44
	v_pk_mul_f32 v[42:43], v[46:47], v[42:43]
	v_pk_mul_f32 v[40:41], v[48:49], v[40:41]
	v_and_b32_sdwa v46, v43, v90 dst_sel:DWORD dst_unused:UNUSED_PAD src0_sel:WORD_1 src1_sel:DWORD
	v_and_b32_sdwa v47, v42, v90 dst_sel:DWORD dst_unused:UNUSED_PAD src0_sel:WORD_1 src1_sel:DWORD
	v_and_b32_sdwa v44, v41, v90 dst_sel:DWORD dst_unused:UNUSED_PAD src0_sel:WORD_1 src1_sel:DWORD
	v_and_b32_sdwa v45, v40, v90 dst_sel:DWORD dst_unused:UNUSED_PAD src0_sel:WORD_1 src1_sel:DWORD
	v_add3_u32 v43, v43, v46, s19
	v_add3_u32 v42, v42, v47, s19
	v_add3_u32 v40, v40, v45, s19
	v_add3_u32 v41, v41, v44, s19
	v_and_b32_e32 v43, 0xffff0000, v43
	v_and_b32_e32 v42, 0xffff0000, v42
	v_or_b32_sdwa v41, v43, v41 dst_sel:DWORD dst_unused:UNUSED_PAD src0_sel:DWORD src1_sel:WORD_1
	v_or_b32_sdwa v40, v42, v40 dst_sel:DWORD dst_unused:UNUSED_PAD src0_sel:DWORD src1_sel:WORD_1
	global_store_dwordx2 v[76:77], v[40:41], off offset:-3072
	v_mov_b32_e32 v40, v120
	v_mov_b32_e32 v41, v121
	v_mov_b32_e32 v42, v122
	v_mov_b32_e32 v43, v123
	v_mov_b32_e32 v44, v36
	v_mov_b32_e32 v45, v38
	v_mov_b32_e32 v38, v37
	v_pk_mul_f32 v[36:37], v[44:45], v[52:53] op_sel_hi:[1,0]
	v_pk_mul_f32 v[38:39], v[38:39], v[52:53] op_sel_hi:[1,0]
	v_mul_f32_e32 v47, v0, v0
	v_mul_f32_e32 v46, v7, v7
	v_mov_b32_e32 v45, v42
	v_mov_b32_e32 v42, v41
	v_mov_b32_e32 v44, v40
	v_pk_mul_f32 v[38:39], v[42:43], v[38:39]
	v_pk_mul_f32 v[36:37], v[44:45], v[36:37]
	v_and_b32_sdwa v42, v39, v90 dst_sel:DWORD dst_unused:UNUSED_PAD src0_sel:WORD_1 src1_sel:DWORD
	v_and_b32_sdwa v43, v38, v90 dst_sel:DWORD dst_unused:UNUSED_PAD src0_sel:WORD_1 src1_sel:DWORD
	v_and_b32_sdwa v40, v37, v90 dst_sel:DWORD dst_unused:UNUSED_PAD src0_sel:WORD_1 src1_sel:DWORD
	v_and_b32_sdwa v41, v36, v90 dst_sel:DWORD dst_unused:UNUSED_PAD src0_sel:WORD_1 src1_sel:DWORD
	v_add3_u32 v39, v39, v42, s19
	v_add3_u32 v38, v38, v43, s19
	v_add3_u32 v36, v36, v41, s19
	v_add3_u32 v37, v37, v40, s19
	v_and_b32_e32 v39, 0xffff0000, v39
	v_and_b32_e32 v38, 0xffff0000, v38
	v_or_b32_sdwa v37, v39, v37 dst_sel:DWORD dst_unused:UNUSED_PAD src0_sel:DWORD src1_sel:WORD_1
	v_or_b32_sdwa v36, v38, v36 dst_sel:DWORD dst_unused:UNUSED_PAD src0_sel:DWORD src1_sel:WORD_1
	global_store_dwordx2 v[76:77], v[36:37], off offset:-2560
	v_mov_b32_e32 v36, v124
	v_mov_b32_e32 v37, v125
	v_mov_b32_e32 v38, v126
	v_mov_b32_e32 v39, v127
	v_mov_b32_e32 v40, v28
	v_mov_b32_e32 v41, v30
	v_mov_b32_e32 v30, v29
	v_pk_mul_f32 v[28:29], v[40:41], v[52:53] op_sel_hi:[1,0]
	v_pk_mul_f32 v[30:31], v[30:31], v[52:53] op_sel_hi:[1,0]
	v_pk_mul_f32 v[42:43], v[8:9], v[8:9]
	v_mul_f32_e32 v44, v5, v5
	v_mul_f32_e32 v52, v3, v3
	v_mov_b32_e32 v41, v38
	v_mov_b32_e32 v38, v37
	v_mov_b32_e32 v40, v36
	v_pk_mul_f32 v[30:31], v[30:31], v[38:39]
	v_pk_mul_f32 v[28:29], v[28:29], v[40:41]
	v_and_b32_sdwa v38, v31, v90 dst_sel:DWORD dst_unused:UNUSED_PAD src0_sel:WORD_1 src1_sel:DWORD
	v_and_b32_sdwa v39, v30, v90 dst_sel:DWORD dst_unused:UNUSED_PAD src0_sel:WORD_1 src1_sel:DWORD
	v_and_b32_sdwa v36, v29, v90 dst_sel:DWORD dst_unused:UNUSED_PAD src0_sel:WORD_1 src1_sel:DWORD
	v_and_b32_sdwa v37, v28, v90 dst_sel:DWORD dst_unused:UNUSED_PAD src0_sel:WORD_1 src1_sel:DWORD
	v_add3_u32 v31, v31, v38, s19
	v_add3_u32 v30, v30, v39, s19
	v_add3_u32 v28, v28, v37, s19
	v_add3_u32 v29, v29, v36, s19
	v_and_b32_e32 v31, 0xffff0000, v31
	v_and_b32_e32 v30, 0xffff0000, v30
	v_or_b32_sdwa v29, v31, v29 dst_sel:DWORD dst_unused:UNUSED_PAD src0_sel:DWORD src1_sel:WORD_1
	v_or_b32_sdwa v28, v30, v28 dst_sel:DWORD dst_unused:UNUSED_PAD src0_sel:DWORD src1_sel:WORD_1
	global_store_dwordx2 v[76:77], v[28:29], off offset:-2048
	v_mov_b32_e32 v28, v112
	v_mov_b32_e32 v29, v113
	v_mov_b32_e32 v30, v114
	v_mov_b32_e32 v31, v115
	v_pk_mul_f32 v[36:37], v[18:19], v[18:19]
	v_pk_mul_f32 v[38:39], v[16:17], v[16:17]
	v_pk_mul_f32 v[40:41], v[10:11], v[10:11]
	v_pk_mov_b32 v[48:49], v[38:39], v[36:37] op_sel:[1,0]
	v_mov_b32_e32 v39, v37
	v_pk_mov_b32 v[36:37], v[42:43], v[40:41] op_sel:[1,0]
	v_mov_b32_e32 v43, v41
	v_pk_add_f32 v[38:39], v[48:49], v[38:39]
	v_pk_add_f32 v[36:37], v[36:37], v[42:43]
	v_pk_fma_f32 v[40:41], v[4:5], v[4:5], v[44:45] op_sel_hi:[1,1,0]
	v_pk_fma_f32 v[44:45], v[6:7], v[6:7], v[46:47] op_sel_hi:[1,1,0]
	v_pk_add_f32 v[38:39], v[38:39], v[38:39] op_sel:[0,1] op_sel_hi:[1,0]
	v_pk_add_f32 v[36:37], v[36:37], v[36:37] op_sel:[0,1] op_sel_hi:[1,0]
	v_mov_b32_e32 v41, v51
	v_mov_b32_e32 v45, v52
	v_mov_b32_e32 v39, v47
	v_mov_b32_e32 v37, v50
	v_pk_add_f32 v[40:41], v[40:41], v[44:45]
	v_pk_add_f32 v[36:37], v[38:39], v[36:37]
	v_mov_b32_e32 v38, v16
	v_pk_add_f32 v[36:37], v[36:37], v[40:41]
	v_mov_b32_e32 v39, v18
	v_add_f32_e32 v36, v36, v37
	ds_bpermute_b32 v37, v80, v36
	v_mov_b32_e32 v18, v17
	s_waitcnt lgkmcnt(0)
; __device__ __forceinline__ unsigned pk2(float lo, float hi) { return f2bf(lo) | (f2bf(hi) << 16); }
; __device__ __forceinline__ float wave_sum(float v) {
; #pragma unroll
;     for (int o = 1; o < 64; o <<= 1) v += __shfl_xor(v, o);
;     return v;
; __device__ __forceinline__ void p0_prologue(const Params& p, LAS unsigned char* lds, int G) {
;     ...
;         for (int q = 0; q < 4; ++q) { float a = 0.f;
; #pragma unroll
;             for (int j = 0; j < 4; ++j) a += (v[q][j][0] * v[q][j][0] + v[q][j][1] * v[q][j][1]) + (v[q][j][2] * v[q][j][2] + v[q][j][3] * v[q][j][3]);
;             s[q] = a; }
; #pragma unroll
;         for (int q = 0; q < 4; ++q) { const float rstd = __builtin_amdgcn_rsqf(wave_sum(s[q]) * (1.f / D) + EPS);
;             u32x2* o8 = (u32x2*)(XN + (size_t)(rb + q) * D) + lane;
; #pragma unroll
;             for (int j = 0; j < 4; ++j) { const f32x4 g = gp[64 * j]; u32x2 w; w.x = pk2(v[q][j][0] * rstd * g[0], v[q][j][1] * rstd * g[1]); w.y = pk2(v[q][j][2] * rstd * g[2], v[q][j][3] * rstd * g[3]); o8[64 * j] = w; } }
	v_add_f32_e32 v36, v36, v37
	ds_bpermute_b32 v37, v81, v36
	s_waitcnt lgkmcnt(0)
	v_add_f32_e32 v36, v36, v37
	ds_bpermute_b32 v37, v82, v36
	s_waitcnt lgkmcnt(0)
	v_add_f32_e32 v36, v36, v37
	ds_bpermute_b32 v37, v83, v36
	s_waitcnt lgkmcnt(0)
	v_add_f32_e32 v36, v36, v37
	ds_bpermute_b32 v37, v84, v36
	s_waitcnt lgkmcnt(0)
	v_add_f32_e32 v36, v36, v37
	ds_bpermute_b32 v37, v85, v36
	s_waitcnt lgkmcnt(0)
	v_add_f32_e32 v36, v36, v37
	v_fmamk_f32 v36, v36, 0x3a800000, v89
	v_rsq_f32_e32 v36, v36
	s_nop 0
	v_pk_mul_f32 v[16:17], v[38:39], v[36:37] op_sel_hi:[1,0]
	v_pk_mul_f32 v[18:19], v[18:19], v[36:37] op_sel_hi:[1,0]
	v_mov_b32_e32 v39, v30
	v_mov_b32_e32 v30, v29
	v_mov_b32_e32 v38, v28
	v_pk_mul_f32 v[18:19], v[30:31], v[18:19]
	v_pk_mul_f32 v[16:17], v[38:39], v[16:17]
	v_and_b32_sdwa v30, v19, v90 dst_sel:DWORD dst_unused:UNUSED_PAD src0_sel:WORD_1 src1_sel:DWORD
	v_and_b32_sdwa v31, v18, v90 dst_sel:DWORD dst_unused:UNUSED_PAD src0_sel:WORD_1 src1_sel:DWORD
	v_and_b32_sdwa v28, v17, v90 dst_sel:DWORD dst_unused:UNUSED_PAD src0_sel:WORD_1 src1_sel:DWORD
	v_and_b32_sdwa v29, v16, v90 dst_sel:DWORD dst_unused:UNUSED_PAD src0_sel:WORD_1 src1_sel:DWORD
	v_add3_u32 v19, v19, v30, s19
	v_add3_u32 v18, v18, v31, s19
	v_add3_u32 v16, v16, v29, s19
	v_add3_u32 v17, v17, v28, s19
	v_and_b32_e32 v19, 0xffff0000, v19
	v_and_b32_e32 v18, 0xffff0000, v18
	v_or_b32_sdwa v17, v19, v17 dst_sel:DWORD dst_unused:UNUSED_PAD src0_sel:DWORD src1_sel:WORD_1
	v_or_b32_sdwa v16, v18, v16 dst_sel:DWORD dst_unused:UNUSED_PAD src0_sel:DWORD src1_sel:WORD_1
	global_store_dwordx2 v[76:77], v[16:17], off offset:-1536
	v_mov_b32_e32 v16, v116
	v_mov_b32_e32 v17, v117
	v_mov_b32_e32 v18, v118
	v_mov_b32_e32 v19, v119
	v_mov_b32_e32 v28, v8
	v_mov_b32_e32 v29, v10
	v_mov_b32_e32 v10, v9
	v_pk_mul_f32 v[8:9], v[28:29], v[36:37] op_sel_hi:[1,0]
	v_pk_mul_f32 v[10:11], v[10:11], v[36:37] op_sel_hi:[1,0]
	v_mul_f32_e32 v30, v13, v13
	v_mul_f32_e32 v31, v14, v14
	v_mov_b32_e32 v29, v18
	v_mov_b32_e32 v18, v17
	v_mov_b32_e32 v28, v16
	v_pk_mul_f32 v[10:11], v[18:19], v[10:11]
	v_pk_mul_f32 v[8:9], v[28:29], v[8:9]
	v_and_b32_sdwa v18, v11, v90 dst_sel:DWORD dst_unused:UNUSED_PAD src0_sel:WORD_1 src1_sel:DWORD
	v_and_b32_sdwa v19, v10, v90 dst_sel:DWORD dst_unused:UNUSED_PAD src0_sel:WORD_1 src1_sel:DWORD
	v_and_b32_sdwa v16, v9, v90 dst_sel:DWORD dst_unused:UNUSED_PAD src0_sel:WORD_1 src1_sel:DWORD
	v_and_b32_sdwa v17, v8, v90 dst_sel:DWORD dst_unused:UNUSED_PAD src0_sel:WORD_1 src1_sel:DWORD
	v_add3_u32 v11, v11, v18, s19
	v_add3_u32 v10, v10, v19, s19
	v_add3_u32 v8, v8, v17, s19
	v_add3_u32 v9, v9, v16, s19
	v_and_b32_e32 v11, 0xffff0000, v11
	v_and_b32_e32 v10, 0xffff0000, v10
	v_or_b32_sdwa v9, v11, v9 dst_sel:DWORD dst_unused:UNUSED_PAD src0_sel:DWORD src1_sel:WORD_1
	v_or_b32_sdwa v8, v10, v8 dst_sel:DWORD dst_unused:UNUSED_PAD src0_sel:DWORD src1_sel:WORD_1
	global_store_dwordx2 v[76:77], v[8:9], off offset:-1024
	v_mov_b32_e32 v8, v120
	v_mov_b32_e32 v9, v121
	v_mov_b32_e32 v10, v122
	v_mov_b32_e32 v11, v123
	v_mov_b32_e32 v16, v4
	v_mov_b32_e32 v17, v6
	v_mov_b32_e32 v6, v5
	v_pk_mul_f32 v[4:5], v[16:17], v[36:37] op_sel_hi:[1,0]
	v_pk_mul_f32 v[6:7], v[6:7], v[36:37] op_sel_hi:[1,0]
	v_mul_f32_e32 v19, v12, v12
	v_mul_f32_e32 v18, v23, v23
	v_mov_b32_e32 v17, v10
	v_mov_b32_e32 v10, v9
	v_mov_b32_e32 v16, v8
	v_pk_mul_f32 v[6:7], v[10:11], v[6:7]
	v_pk_mul_f32 v[4:5], v[16:17], v[4:5]
	v_and_b32_sdwa v10, v7, v90 dst_sel:DWORD dst_unused:UNUSED_PAD src0_sel:WORD_1 src1_sel:DWORD
	v_and_b32_sdwa v11, v6, v90 dst_sel:DWORD dst_unused:UNUSED_PAD src0_sel:WORD_1 src1_sel:DWORD
	v_and_b32_sdwa v8, v5, v90 dst_sel:DWORD dst_unused:UNUSED_PAD src0_sel:WORD_1 src1_sel:DWORD
	v_and_b32_sdwa v9, v4, v90 dst_sel:DWORD dst_unused:UNUSED_PAD src0_sel:WORD_1 src1_sel:DWORD
	v_add3_u32 v7, v7, v10, s19
	v_add3_u32 v6, v6, v11, s19
	v_add3_u32 v4, v4, v9, s19
	v_add3_u32 v5, v5, v8, s19
	v_and_b32_e32 v7, 0xffff0000, v7
	v_and_b32_e32 v6, 0xffff0000, v6
	v_or_b32_sdwa v5, v7, v5 dst_sel:DWORD dst_unused:UNUSED_PAD src0_sel:DWORD src1_sel:WORD_1
	v_or_b32_sdwa v4, v6, v4 dst_sel:DWORD dst_unused:UNUSED_PAD src0_sel:DWORD src1_sel:WORD_1
	global_store_dwordx2 v[76:77], v[4:5], off offset:-512
	v_mov_b32_e32 v4, v124
	v_mov_b32_e32 v5, v125
	v_mov_b32_e32 v6, v126
	v_mov_b32_e32 v7, v127
	v_mov_b32_e32 v8, v0
	v_mov_b32_e32 v9, v2
	v_mov_b32_e32 v2, v1
	v_pk_mul_f32 v[0:1], v[8:9], v[36:37] op_sel_hi:[1,0]
	v_pk_mul_f32 v[2:3], v[2:3], v[36:37] op_sel_hi:[1,0]
	v_pk_mul_f32 v[10:11], v[24:25], v[24:25]
	v_mul_f32_e32 v16, v21, v21
	v_mul_f32_e32 v36, v15, v15
	v_mov_b32_e32 v9, v6
	v_mov_b32_e32 v6, v5
	v_mov_b32_e32 v8, v4
	v_pk_mul_f32 v[2:3], v[2:3], v[6:7]
	v_pk_mul_f32 v[0:1], v[0:1], v[8:9]
	v_and_b32_sdwa v6, v3, v90 dst_sel:DWORD dst_unused:UNUSED_PAD src0_sel:WORD_1 src1_sel:DWORD
	v_and_b32_sdwa v7, v2, v90 dst_sel:DWORD dst_unused:UNUSED_PAD src0_sel:WORD_1 src1_sel:DWORD
	v_and_b32_sdwa v4, v1, v90 dst_sel:DWORD dst_unused:UNUSED_PAD src0_sel:WORD_1 src1_sel:DWORD
	v_and_b32_sdwa v5, v0, v90 dst_sel:DWORD dst_unused:UNUSED_PAD src0_sel:WORD_1 src1_sel:DWORD
	v_add3_u32 v3, v3, v6, s19
	v_add3_u32 v2, v2, v7, s19
	v_add3_u32 v0, v0, v5, s19
	v_add3_u32 v1, v1, v4, s19
	v_and_b32_e32 v3, 0xffff0000, v3
	v_and_b32_e32 v2, 0xffff0000, v2
	v_or_b32_sdwa v1, v3, v1 dst_sel:DWORD dst_unused:UNUSED_PAD src0_sel:DWORD src1_sel:WORD_1
	v_or_b32_sdwa v0, v2, v0 dst_sel:DWORD dst_unused:UNUSED_PAD src0_sel:DWORD src1_sel:WORD_1
	global_store_dwordx2 v[76:77], v[0:1], off
	v_mov_b32_e32 v0, v112
	v_mov_b32_e32 v1, v113
	v_mov_b32_e32 v2, v114
	v_mov_b32_e32 v3, v115
	v_pk_mul_f32 v[4:5], v[34:35], v[34:35]
	v_pk_mul_f32 v[6:7], v[32:33], v[32:33]
	v_pk_mul_f32 v[8:9], v[26:27], v[26:27]
	v_pk_mov_b32 v[28:29], v[6:7], v[4:5] op_sel:[1,0]
	v_mov_b32_e32 v7, v5
	v_pk_mov_b32 v[4:5], v[10:11], v[8:9] op_sel:[1,0]
	v_mov_b32_e32 v11, v9
	v_pk_add_f32 v[6:7], v[28:29], v[6:7]
	v_pk_add_f32 v[4:5], v[4:5], v[10:11]
	v_pk_fma_f32 v[8:9], v[20:21], v[20:21], v[16:17] op_sel_hi:[1,1,0]
	v_pk_fma_f32 v[16:17], v[22:23], v[22:23], v[18:19] op_sel_hi:[1,1,0]
	v_pk_add_f32 v[6:7], v[6:7], v[6:7] op_sel:[0,1] op_sel_hi:[1,0]
	v_pk_add_f32 v[4:5], v[4:5], v[4:5] op_sel:[0,1] op_sel_hi:[1,0]
	v_mov_b32_e32 v9, v31
	v_mov_b32_e32 v17, v36
	v_mov_b32_e32 v7, v19
	v_mov_b32_e32 v5, v30
	v_pk_add_f32 v[8:9], v[8:9], v[16:17]
	v_pk_add_f32 v[4:5], v[6:7], v[4:5]
	v_lshl_add_u64 v[76:77], v[76:77], 0, s[10:11]
	v_pk_add_f32 v[4:5], v[4:5], v[8:9]
	v_mov_b32_e32 v9, v34
	v_add_f32_e32 v4, v4, v5
	ds_bpermute_b32 v5, v80, v4
	v_mov_b32_e32 v34, v33
	v_mov_b32_e32 v8, v32
	s_waitcnt lgkmcnt(0)
; __device__ __forceinline__ unsigned pk2(float lo, float hi) { return f2bf(lo) | (f2bf(hi) << 16); }
; __device__ __forceinline__ float wave_sum(float v) {
; #pragma unroll
;     for (int o = 1; o < 64; o <<= 1) v += __shfl_xor(v, o);
;     return v;
; __device__ __forceinline__ void p0_prologue(const Params& p, LAS unsigned char* lds, int G) {
;     ...
;     for (int rb = gw * 4; rb < T; rb += NGW * 4) {
;         f32x4 v[4][4]; float s[4];
; #pragma unroll
;         for (int q = 0; q < 4; ++q) { const int row = rb + q; const float* xrow = row < TP ? p.in[0] + (size_t)row * D : p.in[1] + (size_t)(row - TP) * D; const f32x4* xr = (const f32x4*)xrow + lane;
; #pragma unroll
;             for (int j = 0; j < 4; ++j) v[q][j] = xr[64 * j]; }
; #pragma unroll
;         for (int q = 0; q < 4; ++q) { float a = 0.f;
; #pragma unroll
;             for (int j = 0; j < 4; ++j) a += (v[q][j][0] * v[q][j][0] + v[q][j][1] * v[q][j][1]) + (v[q][j][2] * v[q][j][2] + v[q][j][3] * v[q][j][3]);
;             s[q] = a; }
; #pragma unroll
;         for (int q = 0; q < 4; ++q) { const float rstd = __builtin_amdgcn_rsqf(wave_sum(s[q]) * (1.f / D) + EPS);
;             u32x2* o8 = (u32x2*)(XN + (size_t)(rb + q) * D) + lane;
; #pragma unroll
;             for (int j = 0; j < 4; ++j) { const f32x4 g = gp[64 * j]; u32x2 w; w.x = pk2(v[q][j][0] * rstd * g[0], v[q][j][1] * rstd * g[1]); w.y = pk2(v[q][j][2] * rstd * g[2], v[q][j][3] * rstd * g[3]); o8[64 * j] = w; } }
;     }
	v_add_f32_e32 v4, v4, v5
	ds_bpermute_b32 v5, v81, v4
	s_waitcnt lgkmcnt(0)
	v_add_f32_e32 v4, v4, v5
	ds_bpermute_b32 v5, v82, v4
	s_waitcnt lgkmcnt(0)
	v_add_f32_e32 v4, v4, v5
	ds_bpermute_b32 v5, v83, v4
	s_waitcnt lgkmcnt(0)
	v_add_f32_e32 v4, v4, v5
	ds_bpermute_b32 v5, v84, v4
	s_waitcnt lgkmcnt(0)
	v_add_f32_e32 v6, v4, v5
	ds_bpermute_b32 v7, v85, v6
	v_lshlrev_b64 v[4:5], 11, v[78:79]
	v_lshl_add_u64 v[4:5], v[70:71], 0, v[4:5]
	s_waitcnt lgkmcnt(0)
	v_add_f32_e32 v6, v6, v7
	v_fmamk_f32 v6, v6, 0x3a800000, v89
	v_rsq_f32_e32 v6, v6
	v_mov_b32_e32 v17, v2
	v_pk_mul_f32 v[10:11], v[34:35], v[6:7] op_sel_hi:[1,0]
	v_mov_b32_e32 v2, v1
	v_pk_mul_f32 v[8:9], v[8:9], v[6:7] op_sel_hi:[1,0]
	v_mov_b32_e32 v16, v0
	v_pk_mul_f32 v[2:3], v[2:3], v[10:11]
	v_pk_mul_f32 v[0:1], v[16:17], v[8:9]
	v_and_b32_sdwa v9, v3, v90 dst_sel:DWORD dst_unused:UNUSED_PAD src0_sel:WORD_1 src1_sel:DWORD
	v_and_b32_sdwa v10, v2, v90 dst_sel:DWORD dst_unused:UNUSED_PAD src0_sel:WORD_1 src1_sel:DWORD
	v_and_b32_sdwa v7, v1, v90 dst_sel:DWORD dst_unused:UNUSED_PAD src0_sel:WORD_1 src1_sel:DWORD
	v_and_b32_sdwa v8, v0, v90 dst_sel:DWORD dst_unused:UNUSED_PAD src0_sel:WORD_1 src1_sel:DWORD
	v_add3_u32 v3, v3, v9, s19
	v_add3_u32 v2, v2, v10, s19
	v_add3_u32 v0, v0, v8, s19
	v_add3_u32 v1, v1, v7, s19
	v_and_b32_e32 v3, 0xffff0000, v3
	v_and_b32_e32 v2, 0xffff0000, v2
	v_or_b32_sdwa v1, v3, v1 dst_sel:DWORD dst_unused:UNUSED_PAD src0_sel:DWORD src1_sel:WORD_1
	v_or_b32_sdwa v0, v2, v0 dst_sel:DWORD dst_unused:UNUSED_PAD src0_sel:DWORD src1_sel:WORD_1
	global_store_dwordx2 v[4:5], v[0:1], off
	v_mov_b32_e32 v0, v116
	v_mov_b32_e32 v1, v117
	v_mov_b32_e32 v2, v118
	v_mov_b32_e32 v3, v119
	v_mov_b32_e32 v9, v26
	v_mov_b32_e32 v26, v25
	v_mov_b32_e32 v8, v24
	v_pk_mul_f32 v[10:11], v[26:27], v[6:7] op_sel_hi:[1,0]
	v_pk_mul_f32 v[8:9], v[8:9], v[6:7] op_sel_hi:[1,0]
	v_mov_b32_e32 v17, v2
	v_mov_b32_e32 v2, v1
	v_mov_b32_e32 v16, v0
	v_pk_mul_f32 v[2:3], v[2:3], v[10:11]
	v_pk_mul_f32 v[0:1], v[16:17], v[8:9]
	v_and_b32_sdwa v9, v3, v90 dst_sel:DWORD dst_unused:UNUSED_PAD src0_sel:WORD_1 src1_sel:DWORD
	v_and_b32_sdwa v10, v2, v90 dst_sel:DWORD dst_unused:UNUSED_PAD src0_sel:WORD_1 src1_sel:DWORD
	v_and_b32_sdwa v7, v1, v90 dst_sel:DWORD dst_unused:UNUSED_PAD src0_sel:WORD_1 src1_sel:DWORD
	v_and_b32_sdwa v8, v0, v90 dst_sel:DWORD dst_unused:UNUSED_PAD src0_sel:WORD_1 src1_sel:DWORD
	v_add3_u32 v3, v3, v9, s19
	v_add3_u32 v2, v2, v10, s19
	v_add3_u32 v0, v0, v8, s19
	v_add3_u32 v1, v1, v7, s19
	v_and_b32_e32 v3, 0xffff0000, v3
	v_and_b32_e32 v2, 0xffff0000, v2
	v_or_b32_sdwa v1, v3, v1 dst_sel:DWORD dst_unused:UNUSED_PAD src0_sel:DWORD src1_sel:WORD_1
	v_or_b32_sdwa v0, v2, v0 dst_sel:DWORD dst_unused:UNUSED_PAD src0_sel:DWORD src1_sel:WORD_1
	global_store_dwordx2 v[4:5], v[0:1], off offset:512
	v_mov_b32_e32 v0, v120
	v_mov_b32_e32 v1, v121
	v_mov_b32_e32 v2, v122
	v_mov_b32_e32 v3, v123
	v_mov_b32_e32 v9, v22
	v_mov_b32_e32 v22, v21
	v_mov_b32_e32 v8, v20
	v_pk_mul_f32 v[10:11], v[22:23], v[6:7] op_sel_hi:[1,0]
	v_pk_mul_f32 v[8:9], v[8:9], v[6:7] op_sel_hi:[1,0]
	v_mov_b32_e32 v17, v2
	v_mov_b32_e32 v2, v1
	v_mov_b32_e32 v16, v0
	v_pk_mul_f32 v[2:3], v[2:3], v[10:11]
	v_pk_mul_f32 v[0:1], v[16:17], v[8:9]
	v_and_b32_sdwa v9, v3, v90 dst_sel:DWORD dst_unused:UNUSED_PAD src0_sel:WORD_1 src1_sel:DWORD
	v_and_b32_sdwa v10, v2, v90 dst_sel:DWORD dst_unused:UNUSED_PAD src0_sel:WORD_1 src1_sel:DWORD
	v_and_b32_sdwa v7, v1, v90 dst_sel:DWORD dst_unused:UNUSED_PAD src0_sel:WORD_1 src1_sel:DWORD
	v_and_b32_sdwa v8, v0, v90 dst_sel:DWORD dst_unused:UNUSED_PAD src0_sel:WORD_1 src1_sel:DWORD
	v_add3_u32 v3, v3, v9, s19
	v_add3_u32 v2, v2, v10, s19
	v_add3_u32 v0, v0, v8, s19
	v_add3_u32 v1, v1, v7, s19
	v_and_b32_e32 v3, 0xffff0000, v3
	v_and_b32_e32 v2, 0xffff0000, v2
	v_or_b32_sdwa v1, v3, v1 dst_sel:DWORD dst_unused:UNUSED_PAD src0_sel:DWORD src1_sel:WORD_1
	v_or_b32_sdwa v0, v2, v0 dst_sel:DWORD dst_unused:UNUSED_PAD src0_sel:DWORD src1_sel:WORD_1
	global_store_dwordx2 v[4:5], v[0:1], off offset:1024
	v_mov_b32_e32 v0, v124
	v_mov_b32_e32 v1, v125
	v_mov_b32_e32 v2, v126
	v_mov_b32_e32 v3, v127
	v_mov_b32_e32 v8, v12
	v_mov_b32_e32 v9, v14
	v_mov_b32_e32 v14, v13
	v_pk_mul_f32 v[8:9], v[8:9], v[6:7] op_sel_hi:[1,0]
	v_pk_mul_f32 v[6:7], v[14:15], v[6:7] op_sel_hi:[1,0]
	v_mov_b32_e32 v11, v2
	v_mov_b32_e32 v2, v1
	v_mov_b32_e32 v10, v0
	v_pk_mul_f32 v[2:3], v[6:7], v[2:3]
	v_pk_mul_f32 v[0:1], v[8:9], v[10:11]
	v_and_b32_sdwa v8, v3, v90 dst_sel:DWORD dst_unused:UNUSED_PAD src0_sel:WORD_1 src1_sel:DWORD
	v_and_b32_sdwa v9, v2, v90 dst_sel:DWORD dst_unused:UNUSED_PAD src0_sel:WORD_1 src1_sel:DWORD
	v_and_b32_sdwa v6, v1, v90 dst_sel:DWORD dst_unused:UNUSED_PAD src0_sel:WORD_1 src1_sel:DWORD
	v_and_b32_sdwa v7, v0, v90 dst_sel:DWORD dst_unused:UNUSED_PAD src0_sel:WORD_1 src1_sel:DWORD
	v_add3_u32 v3, v3, v8, s19
	v_add3_u32 v2, v2, v9, s19
	v_add3_u32 v0, v0, v7, s19
	v_add3_u32 v1, v1, v6, s19
	v_and_b32_e32 v3, 0xffff0000, v3
	v_and_b32_e32 v2, 0xffff0000, v2
	v_or_b32_sdwa v1, v3, v1 dst_sel:DWORD dst_unused:UNUSED_PAD src0_sel:DWORD src1_sel:WORD_1
	v_or_b32_sdwa v0, v2, v0 dst_sel:DWORD dst_unused:UNUSED_PAD src0_sel:DWORD src1_sel:WORD_1
	global_store_dwordx2 v[4:5], v[0:1], off offset:1536
	s_andn2_b64 exec, exec, s[16:17]
	s_cbranch_execz .LBB0_174
